# v54 plus nt on the prologue's bf16 activation stores
# baseline (speedup 1.0000x reference)
; __device__ __forceinline__ unsigned cvt_pk_bf16(float lo, float hi) { unsigned r; asm volatile("v_cvt_pk_bf16_f32 %0, %1, %2" : "=v"(r) : "v"(lo), "v"(hi)); return r; }
; __device__ __forceinline__ float wave_sum(float v) {
; #pragma unroll
;     for (int o = 1; o < 64; o <<= 1) v += __shfl_xor(v, o);
;     return v;
; __device__ __forceinline__ void prologue(const Params& p, LAS unsigned char* lds) {
;     ...
;             for (int r = 0; r < 4; ++r) { const int m = m0 + r * NGW;
;                 if (m < MREAL) { float s = 0.f; u32x2* o8 = (u32x2*)(XB + (size_t)m * DM) + lane;
; #pragma unroll
;                     for (int j = 0; j < 4; ++j) { s += (v[r][j][0] * v[r][j][0] + v[r][j][1] * v[r][j][1]) + (v[r][j][2] * v[r][j][2] + v[r][j][3] * v[r][j][3]);
;                         u32x2 w; w.x = cvt_pk_bf16(v[r][j][0], v[r][j][1]); w.y = cvt_pk_bf16(v[r][j][2], v[r][j][3]); o8[64 * j] = w; }
;                     s = wave_sum(s);
;                     if (lane == 0) ssq[m] = s; } }
.LBB0_75:
	s_waitcnt vmcnt(3)
	v_mul_f32_e32 v70, v61, v61
	v_mul_f32_e32 v71, v63, v63
	v_fmac_f32_e32 v70, v60, v60
	v_fmac_f32_e32 v71, v62, v62
	v_add_f32_e32 v70, v70, v71
	s_waitcnt vmcnt(2)
	v_mul_f32_e32 v71, v57, v57
	v_mul_f32_e32 v72, v59, v59
	v_fmac_f32_e32 v71, v56, v56
	v_fmac_f32_e32 v72, v58, v58
	v_add_f32_e32 v71, v71, v72
	v_add_f32_e32 v70, v70, v71
	s_waitcnt vmcnt(1)
	v_mul_f32_e32 v71, v53, v53
	v_mul_f32_e32 v72, v55, v55
	v_fmac_f32_e32 v71, v52, v52
	v_fmac_f32_e32 v72, v54, v54
	v_add_f32_e32 v71, v71, v72
	v_add_f32_e32 v70, v70, v71
	s_waitcnt vmcnt(0)
	v_mul_f32_e32 v71, v49, v49
	v_mul_f32_e32 v72, v51, v51
	v_fmac_f32_e32 v71, v48, v48
	v_fmac_f32_e32 v72, v50, v50
	v_add_f32_e32 v71, v71, v72
	v_add_f32_e32 v71, v70, v71
	v_and_b32_e32 v70, 64, v69
	v_add_u32_e32 v76, 64, v70
	v_xor_b32_e32 v70, 1, v69
	v_cmp_lt_i32_e32 vcc, v70, v76
	s_lshl_b64 s[20:21], s[0:1], 11
	v_lshl_add_u64 v[74:75], v[66:67], 0, s[20:21]
	v_cndmask_b32_e32 v70, v69, v70, vcc
	v_lshlrev_b32_e32 v70, 2, v70
	ds_bpermute_b32 v72, v70, v71
	v_cvt_pk_bf16_f32 v60, v60, v61
	v_cvt_pk_bf16_f32 v61, v62, v63
	global_store_dwordx2 v[74:75], v[60:61], off nt
	v_cvt_pk_bf16_f32 v60, v56, v57
	s_waitcnt lgkmcnt(0)
	v_add_f32_e32 v72, v71, v72
	v_xor_b32_e32 v71, 2, v69
	v_cmp_lt_i32_e32 vcc, v71, v76
	v_xor_b32_e32 v56, 16, v69
	v_cvt_pk_bf16_f32 v61, v58, v59
	global_store_dwordx2 v[74:75], v[60:61], off offset:512 nt
	v_cndmask_b32_e32 v71, v69, v71, vcc
	v_lshlrev_b32_e32 v71, 2, v71
	ds_bpermute_b32 v73, v71, v72
	v_cvt_pk_bf16_f32 v58, v52, v53
	v_xor_b32_e32 v52, 32, v69
	v_cvt_pk_bf16_f32 v59, v54, v55
	global_store_dwordx2 v[74:75], v[58:59], off offset:1024 nt
	s_waitcnt lgkmcnt(0)
	v_add_f32_e32 v73, v72, v73
	v_xor_b32_e32 v72, 4, v69
	v_cmp_lt_i32_e32 vcc, v72, v76
	v_cvt_pk_bf16_f32 v48, v48, v49
	v_cvt_pk_bf16_f32 v49, v50, v51
	global_store_dwordx2 v[74:75], v[48:49], off offset:1536 nt
	s_nop 0
	v_cndmask_b32_e32 v72, v69, v72, vcc
	v_lshlrev_b32_e32 v72, 2, v72
	ds_bpermute_b32 v77, v72, v73
	s_waitcnt lgkmcnt(0)
	v_add_f32_e32 v77, v73, v77
	v_xor_b32_e32 v73, 8, v69
	v_cmp_lt_i32_e32 vcc, v73, v76
	s_nop 1
	v_cndmask_b32_e32 v73, v69, v73, vcc
	v_lshlrev_b32_e32 v73, 2, v73
	ds_bpermute_b32 v78, v73, v77
	v_cmp_lt_i32_e32 vcc, v56, v76
	s_waitcnt lgkmcnt(0)
	v_add_f32_e32 v57, v77, v78
	v_cndmask_b32_e32 v56, v69, v56, vcc
	v_lshlrev_b32_e32 v56, 2, v56
	ds_bpermute_b32 v62, v56, v57
	v_cmp_lt_i32_e32 vcc, v52, v76
	s_waitcnt lgkmcnt(0)
	v_add_f32_e32 v53, v57, v62
	v_cndmask_b32_e32 v52, v69, v52, vcc
	v_lshlrev_b32_e32 v52, 2, v52
	ds_bpermute_b32 v54, v52, v53
	s_and_saveexec_b64 s[20:21], s[4:5]
	s_cbranch_execz .LBB0_81
	s_lshl_b64 s[0:1], s[0:1], 2
	s_add_u32 s0, s50, s0
	s_waitcnt lgkmcnt(0)
	v_add_f32_e32 v48, v53, v54
	s_addc_u32 s1, s51, s1
	global_store_dword v65, v48, s[0:1]
	s_or_b64 exec, exec, s[20:21]
	s_andn2_b64 vcc, exec, s[18:19]
	s_cbranch_vccz .LBB0_82

; __device__ __forceinline__ unsigned cvt_pk_bf16(float lo, float hi) { unsigned r; asm volatile("v_cvt_pk_bf16_f32 %0, %1, %2" : "=v"(r) : "v"(lo), "v"(hi)); return r; }
; __device__ __forceinline__ float wave_sum(float v) {
; #pragma unroll
;     for (int o = 1; o < 64; o <<= 1) v += __shfl_xor(v, o);
;     return v;
; __device__ __forceinline__ void prologue(const Params& p, LAS unsigned char* lds) {
;     ...
;             for (int r = 0; r < 4; ++r) { const int m = m0 + r * NGW;
;                 if (m < MREAL) { float s = 0.f; u32x2* o8 = (u32x2*)(XB + (size_t)m * DM) + lane;
; #pragma unroll
;                     for (int j = 0; j < 4; ++j) { s += (v[r][j][0] * v[r][j][0] + v[r][j][1] * v[r][j][1]) + (v[r][j][2] * v[r][j][2] + v[r][j][3] * v[r][j][3]);
;                         u32x2 w; w.x = cvt_pk_bf16(v[r][j][0], v[r][j][1]); w.y = cvt_pk_bf16(v[r][j][2], v[r][j][3]); o8[64 * j] = w; }
;                     s = wave_sum(s);
;                     if (lane == 0) ssq[m] = s; } }
.LBB0_78:
	v_mul_f32_e32 v48, v29, v29
	s_waitcnt lgkmcnt(0)
	v_mul_f32_e32 v49, v31, v31
	v_fmac_f32_e32 v48, v28, v28
	v_fmac_f32_e32 v49, v30, v30
	v_add_f32_e32 v48, v48, v49
	v_mul_f32_e32 v49, v25, v25
	v_mul_f32_e32 v50, v27, v27
	v_fmac_f32_e32 v49, v24, v24
	v_fmac_f32_e32 v50, v26, v26
	v_add_f32_e32 v49, v49, v50
	v_add_f32_e32 v48, v49, v48
	v_mul_f32_e32 v49, v21, v21
	v_mul_f32_e32 v50, v23, v23
	v_fmac_f32_e32 v49, v20, v20
	v_fmac_f32_e32 v50, v22, v22
	v_add_f32_e32 v49, v49, v50
	v_add_f32_e32 v48, v49, v48
	v_mul_f32_e32 v49, v17, v17
	v_mul_f32_e32 v50, v19, v19
	v_fmac_f32_e32 v49, v16, v16
	v_fmac_f32_e32 v50, v18, v18
	v_add_f32_e32 v49, v49, v50
	v_add_f32_e32 v48, v49, v48
	ds_bpermute_b32 v49, v70, v48
	s_ashr_i32 s13, s12, 31
	s_lshl_b64 s[0:1], s[12:13], 11
	v_lshl_add_u64 v[50:51], v[66:67], 0, s[0:1]
	s_waitcnt lgkmcnt(0)
	v_add_f32_e32 v48, v48, v49
	ds_bpermute_b32 v49, v71, v48
	s_waitcnt lgkmcnt(0)
	v_add_f32_e32 v48, v48, v49
	ds_bpermute_b32 v49, v72, v48
	s_waitcnt lgkmcnt(0)
	v_add_f32_e32 v53, v48, v49
	ds_bpermute_b32 v54, v73, v53
	v_cvt_pk_bf16_f32 v48, v28, v29
	v_cvt_pk_bf16_f32 v49, v30, v31
	global_store_dwordx2 v[50:51], v[48:49], off nt
	v_cvt_pk_bf16_f32 v48, v24, v25
	s_waitcnt lgkmcnt(0)
	v_add_f32_e32 v53, v53, v54
	ds_bpermute_b32 v57, v56, v53
	v_cvt_pk_bf16_f32 v49, v26, v27
	global_store_dwordx2 v[50:51], v[48:49], off offset:512 nt
	v_cvt_pk_bf16_f32 v54, v20, v21
	v_cvt_pk_bf16_f32 v55, v22, v23
	s_waitcnt lgkmcnt(0)
	v_add_f32_e32 v48, v53, v57
	ds_bpermute_b32 v49, v52, v48
	global_store_dwordx2 v[50:51], v[54:55], off offset:1024 nt
	v_cvt_pk_bf16_f32 v54, v16, v17
	v_cvt_pk_bf16_f32 v55, v18, v19
	global_store_dwordx2 v[50:51], v[54:55], off offset:1536 nt
	s_and_saveexec_b64 s[0:1], s[4:5]
	s_cbranch_execz .LBB0_80
	s_lshl_b64 s[12:13], s[12:13], 2
	s_add_u32 s12, s50, s12
	s_waitcnt lgkmcnt(0)
	v_add_f32_e32 v48, v48, v49
	s_addc_u32 s13, s51, s13
	global_store_dword v65, v48, s[12:13]

; __device__ __forceinline__ unsigned cvt_pk_bf16(float lo, float hi) { unsigned r; asm volatile("v_cvt_pk_bf16_f32 %0, %1, %2" : "=v"(r) : "v"(lo), "v"(hi)); return r; }
; __device__ __forceinline__ float wave_sum(float v) {
; #pragma unroll
;     for (int o = 1; o < 64; o <<= 1) v += __shfl_xor(v, o);
;     return v;
; __device__ __forceinline__ void prologue(const Params& p, LAS unsigned char* lds) {
;     ...
;             for (int r = 0; r < 4; ++r) { const int m = m0 + r * NGW;
;                 if (m < MREAL) { float s = 0.f; u32x2* o8 = (u32x2*)(XB + (size_t)m * DM) + lane;
; #pragma unroll
;                     for (int j = 0; j < 4; ++j) { s += (v[r][j][0] * v[r][j][0] + v[r][j][1] * v[r][j][1]) + (v[r][j][2] * v[r][j][2] + v[r][j][3] * v[r][j][3]);
;                         u32x2 w; w.x = cvt_pk_bf16(v[r][j][0], v[r][j][1]); w.y = cvt_pk_bf16(v[r][j][2], v[r][j][3]); o8[64 * j] = w; }
;                     s = wave_sum(s);
;                     if (lane == 0) ssq[m] = s; } }
.LBB0_82:
	v_mul_f32_e32 v48, v45, v45
	v_mul_f32_e32 v49, v47, v47
	v_fmac_f32_e32 v48, v44, v44
	v_fmac_f32_e32 v49, v46, v46
	v_add_f32_e32 v48, v48, v49
	v_mul_f32_e32 v49, v41, v41
	v_mul_f32_e32 v50, v43, v43
	v_fmac_f32_e32 v49, v40, v40
	v_fmac_f32_e32 v50, v42, v42
	v_add_f32_e32 v49, v49, v50
	v_add_f32_e32 v48, v49, v48
	v_mul_f32_e32 v49, v37, v37
	v_mul_f32_e32 v50, v39, v39
	v_fmac_f32_e32 v49, v36, v36
	v_fmac_f32_e32 v50, v38, v38
	v_add_f32_e32 v49, v49, v50
	v_add_f32_e32 v48, v49, v48
	v_mul_f32_e32 v49, v33, v33
	v_mul_f32_e32 v50, v35, v35
	v_fmac_f32_e32 v49, v32, v32
	v_fmac_f32_e32 v50, v34, v34
	v_add_f32_e32 v49, v49, v50
	v_add_f32_e32 v48, v49, v48
	ds_bpermute_b32 v49, v70, v48
	s_ashr_i32 s9, s8, 31
	s_lshl_b64 s[0:1], s[8:9], 11
	v_lshl_add_u64 v[50:51], v[66:67], 0, s[0:1]
	s_waitcnt lgkmcnt(0)
	v_add_f32_e32 v48, v48, v49
	ds_bpermute_b32 v49, v71, v48
	s_waitcnt lgkmcnt(0)
	v_add_f32_e32 v48, v48, v49
	ds_bpermute_b32 v49, v72, v48
	s_waitcnt lgkmcnt(0)
	v_add_f32_e32 v53, v48, v49
	ds_bpermute_b32 v54, v73, v53
	v_cvt_pk_bf16_f32 v48, v44, v45
	v_cvt_pk_bf16_f32 v49, v46, v47
	global_store_dwordx2 v[50:51], v[48:49], off nt
	v_cvt_pk_bf16_f32 v48, v40, v41
	s_waitcnt lgkmcnt(0)
	v_add_f32_e32 v53, v53, v54
	ds_bpermute_b32 v57, v56, v53
	v_cvt_pk_bf16_f32 v49, v42, v43
	global_store_dwordx2 v[50:51], v[48:49], off offset:512 nt
	v_cvt_pk_bf16_f32 v54, v36, v37
	v_cvt_pk_bf16_f32 v55, v38, v39
	s_waitcnt lgkmcnt(0)
	v_add_f32_e32 v48, v53, v57
	ds_bpermute_b32 v49, v52, v48
	global_store_dwordx2 v[50:51], v[54:55], off offset:1024 nt
	v_cvt_pk_bf16_f32 v54, v32, v33
	v_cvt_pk_bf16_f32 v55, v34, v35
	global_store_dwordx2 v[50:51], v[54:55], off offset:1536 nt
	s_and_saveexec_b64 s[0:1], s[4:5]
	s_cbranch_execz .LBB0_84
	s_lshl_b64 s[18:19], s[8:9], 2
	s_add_u32 s18, s50, s18
	s_waitcnt lgkmcnt(0)
	v_add_f32_e32 v48, v48, v49
	s_addc_u32 s19, s51, s19
	global_store_dword v65, v48, s[18:19]

; __device__ __forceinline__ unsigned cvt_pk_bf16(float lo, float hi) { unsigned r; asm volatile("v_cvt_pk_bf16_f32 %0, %1, %2" : "=v"(r) : "v"(lo), "v"(hi)); return r; }
; __device__ __forceinline__ float wave_sum(float v) {
; #pragma unroll
;     for (int o = 1; o < 64; o <<= 1) v += __shfl_xor(v, o);
;     return v;
; __device__ __forceinline__ void prologue(const Params& p, LAS unsigned char* lds) {
;     ...
;             for (int r = 0; r < 4; ++r) { const int m = m0 + r * NGW;
;                 if (m < MREAL) { float s = 0.f; u32x2* o8 = (u32x2*)(XB + (size_t)m * DM) + lane;
; #pragma unroll
;                     for (int j = 0; j < 4; ++j) { s += (v[r][j][0] * v[r][j][0] + v[r][j][1] * v[r][j][1]) + (v[r][j][2] * v[r][j][2] + v[r][j][3] * v[r][j][3]);
;                         u32x2 w; w.x = cvt_pk_bf16(v[r][j][0], v[r][j][1]); w.y = cvt_pk_bf16(v[r][j][2], v[r][j][3]); o8[64 * j] = w; }
;                     s = wave_sum(s);
;                     if (lane == 0) ssq[m] = s; } }
.LBB0_86:
	v_mul_f32_e32 v48, v13, v13
	s_waitcnt lgkmcnt(0)
	v_mul_f32_e32 v49, v15, v15
	v_fmac_f32_e32 v48, v12, v12
	v_fmac_f32_e32 v49, v14, v14
	v_add_f32_e32 v48, v48, v49
	v_mul_f32_e32 v49, v9, v9
	v_mul_f32_e32 v50, v11, v11
	v_fmac_f32_e32 v49, v8, v8
	v_fmac_f32_e32 v50, v10, v10
	v_add_f32_e32 v49, v49, v50
	v_add_f32_e32 v48, v49, v48
	v_mul_f32_e32 v49, v5, v5
	v_mul_f32_e32 v50, v7, v7
	v_fmac_f32_e32 v49, v4, v4
	v_fmac_f32_e32 v50, v6, v6
	v_add_f32_e32 v49, v49, v50
	v_add_f32_e32 v48, v49, v48
	v_mul_f32_e32 v49, v1, v1
	v_mul_f32_e32 v50, v3, v3
	v_fmac_f32_e32 v49, v0, v0
	v_fmac_f32_e32 v50, v2, v2
	v_add_f32_e32 v49, v49, v50
	v_add_f32_e32 v48, v49, v48
	ds_bpermute_b32 v49, v70, v48
	s_ashr_i32 s11, s10, 31
	s_lshl_b64 s[0:1], s[10:11], 11
	v_lshl_add_u64 v[50:51], v[66:67], 0, s[0:1]
	s_waitcnt lgkmcnt(0)
	v_add_f32_e32 v48, v48, v49
	ds_bpermute_b32 v49, v71, v48
	s_waitcnt lgkmcnt(0)
	v_add_f32_e32 v48, v48, v49
	ds_bpermute_b32 v49, v72, v48
	s_waitcnt lgkmcnt(0)
	v_add_f32_e32 v53, v48, v49
	ds_bpermute_b32 v54, v73, v53
	v_cvt_pk_bf16_f32 v48, v12, v13
	v_cvt_pk_bf16_f32 v49, v14, v15
	global_store_dwordx2 v[50:51], v[48:49], off nt
	v_cvt_pk_bf16_f32 v48, v8, v9
	s_waitcnt lgkmcnt(0)
	v_add_f32_e32 v53, v53, v54
	ds_bpermute_b32 v56, v56, v53
	v_cvt_pk_bf16_f32 v49, v10, v11
	global_store_dwordx2 v[50:51], v[48:49], off offset:512 nt
	v_cvt_pk_bf16_f32 v54, v4, v5
	v_cvt_pk_bf16_f32 v55, v6, v7
	s_waitcnt lgkmcnt(0)
	v_add_f32_e32 v48, v53, v56
	ds_bpermute_b32 v49, v52, v48
	global_store_dwordx2 v[50:51], v[54:55], off offset:1024 nt
	v_cvt_pk_bf16_f32 v52, v0, v1
	v_cvt_pk_bf16_f32 v53, v2, v3
	global_store_dwordx2 v[50:51], v[52:53], off offset:1536 nt
	s_and_saveexec_b64 s[0:1], s[4:5]
	s_cbranch_execz .LBB0_67
	s_lshl_b64 s[10:11], s[10:11], 2
	s_add_u32 s10, s50, s10
	s_waitcnt lgkmcnt(0)
	v_add_f32_e32 v48, v48, v49
	s_addc_u32 s11, s51, s11
	global_store_dword v65, v48, s[10:11]
	s_branch .LBB0_67
